# up GEMM: epilogues of the two wave halves no longer aligned (the leading half takes its extra barrier only before the last unit's epilogue); test on top of v59
# baseline (speedup 1.0000x reference)
; #define PG8_STAGE(bufoff, gbase, voff) do { _Pragma("unroll") for (int _i = 0; _i < 2; ++_i) \
;         __builtin_amdgcn_global_load_lds((const unsigned*)((const char*)(gbase) + (voff)[_i]), (PG8_LAS unsigned*)(lds + (bufoff) + ldsw + _i * 8192), 16, 0, 0); } while (0)
; #define PG8_LDA(dst, b, h) do { _Pragma("unroll") for (int m = 0; m < 4; ++m) _Pragma("unroll") for (int k = 0; k < 2; ++k) dst[m][k] = *(const PG8_LAS bf16x8*)(lds + PG8_SA(b, h) + aoff + m * 2048 + k * 1024); } while (0)
; #define PG8_LDB(dst, b, h) do { _Pragma("unroll") for (int n = 0; n < 2; ++n) _Pragma("unroll") for (int k = 0; k < 2; ++k) dst[n][k] = *(const PG8_LAS bf16x8*)(lds + PG8_SB(b, h) + boff + n * 2048 + k * 1024); } while (0)
; #define PG8_MMA(ai, bj, At, Bt) do { __builtin_amdgcn_s_setprio(1); _Pragma("unroll") for (int m = 0; m < 4; ++m) _Pragma("unroll") for (int n = 0; n < 2; ++n) _Pragma("unroll") for (int k = 0; k < 2; ++k) \
;         acc[ai][bj][m][n] = __builtin_amdgcn_mfma_f32_16x16x32_bf16(Bt[n][k], At[m][k], acc[ai][bj][m][n], 0, 0, 0); __builtin_amdgcn_s_setprio(0); } while (0)
; #define PG8_WAIT_V(n) asm volatile("s_waitcnt vmcnt(" #n ")" ::: "memory")
; #define PG8_WAIT_L(n) asm volatile("s_waitcnt lgkmcnt(" #n ")" ::: "memory")
; template <class Epi, class Sched, bool ALIGN_EPI = false, bool SP2 = false>
; __device__ __forceinline__ void gemm_phase(PG8_LAS unsigned char* lds, const Gemm g, const Sched& S, const Epi& E) {
;     ...
;             const bool last = (t == nt - 2);
;             const char* a1 = cA + (size_t)(t + 1) * kstep;
;             const char* a2 = last ? nA : cA + (size_t)(t + 2) * kstep; const char* b2 = last ? nB : cB + (size_t)(t + 2) * kstep;
;             const char* a3 = a2 + kstep; const char* b3 = b2 + kstep;
;             if (last && has_next) S.a_ready(nxt);
;             if constexpr (SP2) {
;             PG8_LDB(B0, 0, 0); PG8_LDB(B1, 0, 1); PG8_SCHED; PG8_LDA(At, 0, 0); PG8_STAGE(PG8_SA(1, 1), a1 + hstep, voffA);
;             PG8_WAIT_V(8); PG8_WAIT_L(0); PG8_BAR; PG8_MMA(0, 0, At, B0); PG8_MMA(0, 1, At, B1); PG8_BAR; PG8_SCHED;
;             PG8_LDA(At, 0, 1); PG8_STAGE(PG8_SB(0, 0), b2, voffB); PG8_STAGE(PG8_SB(0, 1), b2 + hstep, voffB); PG8_STAGE(PG8_SA(0, 0), a2, voffA);
;             PG8_WAIT_V(8); PG8_WAIT_L(0); PG8_BAR; PG8_MMA(1, 0, At, B0); PG8_MMA(1, 1, At, B1); PG8_BAR; PG8_SCHED;
.LBB0_446:
	ds_read_b128 v[140:143], v254
	ds_read_b128 v[168:171], v254 offset:1024
	ds_read_b128 v[172:175], v254 offset:2048
	ds_read_b128 v[176:179], v254 offset:3072
	ds_read_b128 v[180:183], v254 offset:16384
	ds_read_b128 v[184:187], v254 offset:17408
	ds_read_b128 v[188:191], v254 offset:18432
	ds_read_b128 v[210:213], v254 offset:19456
	s_add_u32 s16, s14, 0xfffc0080
	s_addc_u32 s17, s15, -1
	s_cmp_eq_u32 s53, 12
	s_cselect_b32 s19, s7, s17
	s_cselect_b32 s18, s49, s16
	s_cselect_b32 s17, s5, s52
	s_cselect_b32 s16, s50, s51
	s_mov_b32 m0, s43
	ds_read_b128 v[214:217], v165
	ds_read_b128 v[218:221], v165 offset:1024
	ds_read_b128 v[222:225], v165 offset:2048
	ds_read_b128 v[226:229], v165 offset:3072
	ds_read_b128 v[230:233], v165 offset:4096
	ds_read_b128 v[234:237], v165 offset:5120
	ds_read_b128 v[238:241], v165 offset:6144
	ds_read_b128 v[242:245], v165 offset:7168
	global_load_lds_dwordx4 v136, s[14:15]
	s_mov_b32 m0, s44
	s_nop 0
	global_load_lds_dwordx4 v138, s[14:15]
	s_waitcnt vmcnt(8)
	s_waitcnt lgkmcnt(0)
	s_barrier
	s_setprio 1
	v_mfma_f32_16x16x32_bf16 v[124:127], v[140:143], v[214:217], v[124:127]
	v_mfma_f32_16x16x32_bf16 v[116:119], v[172:175], v[214:217], v[116:119]
	v_mfma_f32_16x16x32_bf16 v[108:111], v[140:143], v[222:225], v[108:111]
	v_mfma_f32_16x16x32_bf16 v[100:103], v[172:175], v[222:225], v[100:103]
	v_mfma_f32_16x16x32_bf16 v[92:95], v[140:143], v[230:233], v[92:95]
	v_mfma_f32_16x16x32_bf16 v[84:87], v[172:175], v[230:233], v[84:87]
	v_mfma_f32_16x16x32_bf16 v[76:79], v[140:143], v[238:241], v[76:79]
	v_mfma_f32_16x16x32_bf16 v[68:71], v[172:175], v[238:241], v[68:71]
	v_mfma_f32_16x16x32_bf16 v[124:127], v[168:171], v[218:221], v[124:127]
	v_mfma_f32_16x16x32_bf16 v[116:119], v[176:179], v[218:221], v[116:119]
	v_mfma_f32_16x16x32_bf16 v[108:111], v[168:171], v[226:229], v[108:111]
	v_mfma_f32_16x16x32_bf16 v[100:103], v[176:179], v[226:229], v[100:103]
	v_mfma_f32_16x16x32_bf16 v[92:95], v[168:171], v[234:237], v[92:95]
	v_mfma_f32_16x16x32_bf16 v[84:87], v[176:179], v[234:237], v[84:87]
	v_mfma_f32_16x16x32_bf16 v[76:79], v[168:171], v[242:245], v[76:79]
	v_mfma_f32_16x16x32_bf16 v[68:71], v[176:179], v[242:245], v[68:71]
	v_mfma_f32_16x16x32_bf16 v[120:123], v[180:183], v[214:217], v[120:123]
	v_mfma_f32_16x16x32_bf16 v[112:115], v[188:191], v[214:217], v[112:115]
	v_mfma_f32_16x16x32_bf16 v[104:107], v[180:183], v[222:225], v[104:107]
	v_mfma_f32_16x16x32_bf16 v[96:99], v[188:191], v[222:225], v[96:99]
	v_mfma_f32_16x16x32_bf16 v[88:91], v[180:183], v[230:233], v[88:91]
	v_mfma_f32_16x16x32_bf16 v[80:83], v[188:191], v[230:233], v[80:83]
	v_mfma_f32_16x16x32_bf16 v[72:75], v[180:183], v[238:241], v[72:75]
	v_mfma_f32_16x16x32_bf16 v[64:67], v[188:191], v[238:241], v[64:67]
	v_mfma_f32_16x16x32_bf16 v[120:123], v[184:187], v[218:221], v[120:123]
	v_mfma_f32_16x16x32_bf16 v[112:115], v[210:213], v[218:221], v[112:115]
	v_mfma_f32_16x16x32_bf16 v[104:107], v[184:187], v[226:229], v[104:107]
	v_mfma_f32_16x16x32_bf16 v[96:99], v[210:213], v[226:229], v[96:99]
	v_mfma_f32_16x16x32_bf16 v[88:91], v[184:187], v[234:237], v[88:91]
	v_mfma_f32_16x16x32_bf16 v[80:83], v[210:213], v[234:237], v[80:83]
	v_mfma_f32_16x16x32_bf16 v[72:75], v[184:187], v[242:245], v[72:75]
	v_mfma_f32_16x16x32_bf16 v[64:67], v[210:213], v[242:245], v[64:67]
	s_setprio 0
	s_barrier
	s_mov_b32 m0, s27
	s_add_u32 s54, s16, 0x40000
	s_addc_u32 s55, s17, 0
	ds_read_b128 v[214:217], v165 offset:16384
	ds_read_b128 v[218:221], v165 offset:17408
	ds_read_b128 v[222:225], v165 offset:18432
	ds_read_b128 v[226:229], v165 offset:19456
	ds_read_b128 v[230:233], v165 offset:20480
	ds_read_b128 v[234:237], v165 offset:21504
	ds_read_b128 v[238:241], v165 offset:22528
	ds_read_b128 v[242:245], v165 offset:23552
	global_load_lds_dwordx4 v132, s[16:17]
	s_mov_b32 m0, s28
	s_nop 0
	global_load_lds_dwordx4 v128, s[16:17]
	s_mov_b32 m0, s29
	s_nop 0
	global_load_lds_dwordx4 v132, s[54:55]
	s_mov_b32 m0, s30
	s_nop 0
	global_load_lds_dwordx4 v128, s[54:55]
	s_mov_b32 m0, s22
	s_nop 0
	global_load_lds_dwordx4 v134, s[18:19]
	s_mov_b32 m0, s31
	s_nop 0
	global_load_lds_dwordx4 v130, s[18:19]
	s_waitcnt vmcnt(8)
	s_waitcnt lgkmcnt(0)
	s_barrier
	s_setprio 1
	v_mfma_f32_16x16x32_bf16 v[60:63], v[140:143], v[214:217], v[60:63]
	v_mfma_f32_16x16x32_bf16 v[52:55], v[172:175], v[214:217], v[52:55]
	v_mfma_f32_16x16x32_bf16 v[44:47], v[140:143], v[222:225], v[44:47]
	v_mfma_f32_16x16x32_bf16 v[36:39], v[172:175], v[222:225], v[36:39]
	v_mfma_f32_16x16x32_bf16 v[28:31], v[140:143], v[230:233], v[28:31]
	v_mfma_f32_16x16x32_bf16 v[20:23], v[172:175], v[230:233], v[20:23]
	v_mfma_f32_16x16x32_bf16 v[12:15], v[140:143], v[238:241], v[12:15]
	v_mfma_f32_16x16x32_bf16 v[4:7], v[172:175], v[238:241], v[4:7]
	v_mfma_f32_16x16x32_bf16 v[60:63], v[168:171], v[218:221], v[60:63]
	v_mfma_f32_16x16x32_bf16 v[52:55], v[176:179], v[218:221], v[52:55]
	v_mfma_f32_16x16x32_bf16 v[44:47], v[168:171], v[226:229], v[44:47]
	v_mfma_f32_16x16x32_bf16 v[36:39], v[176:179], v[226:229], v[36:39]
	v_mfma_f32_16x16x32_bf16 v[28:31], v[168:171], v[234:237], v[28:31]
	v_mfma_f32_16x16x32_bf16 v[20:23], v[176:179], v[234:237], v[20:23]
	v_mfma_f32_16x16x32_bf16 v[12:15], v[168:171], v[242:245], v[12:15]
	v_mfma_f32_16x16x32_bf16 v[4:7], v[176:179], v[242:245], v[4:7]
	v_mfma_f32_16x16x32_bf16 v[56:59], v[180:183], v[214:217], v[56:59]
	v_mfma_f32_16x16x32_bf16 v[48:51], v[188:191], v[214:217], v[48:51]
	v_mfma_f32_16x16x32_bf16 v[40:43], v[180:183], v[222:225], v[40:43]
	v_mfma_f32_16x16x32_bf16 v[32:35], v[188:191], v[222:225], v[32:35]
	v_mfma_f32_16x16x32_bf16 v[24:27], v[180:183], v[230:233], v[24:27]
	v_mfma_f32_16x16x32_bf16 v[16:19], v[188:191], v[230:233], v[16:19]
	v_mfma_f32_16x16x32_bf16 v[8:11], v[180:183], v[238:241], v[8:11]
	v_mfma_f32_16x16x32_bf16 v[0:3], v[188:191], v[238:241], v[0:3]
	v_mfma_f32_16x16x32_bf16 v[56:59], v[184:187], v[218:221], v[56:59]
	v_mfma_f32_16x16x32_bf16 v[48:51], v[210:213], v[218:221], v[48:51]
	v_mfma_f32_16x16x32_bf16 v[40:43], v[184:187], v[226:229], v[40:43]
	v_mfma_f32_16x16x32_bf16 v[32:35], v[210:213], v[226:229], v[32:35]
	v_mfma_f32_16x16x32_bf16 v[24:27], v[184:187], v[234:237], v[24:27]
	v_mfma_f32_16x16x32_bf16 v[16:19], v[210:213], v[234:237], v[16:19]
	v_mfma_f32_16x16x32_bf16 v[8:11], v[184:187], v[242:245], v[8:11]
	v_mfma_f32_16x16x32_bf16 v[0:3], v[210:213], v[242:245], v[0:3]
	s_setprio 0
	s_barrier
; #define PG8_STAGE(bufoff, gbase, voff) do { _Pragma("unroll") for (int _i = 0; _i < 2; ++_i) \
;         __builtin_amdgcn_global_load_lds((const unsigned*)((const char*)(gbase) + (voff)[_i]), (PG8_LAS unsigned*)(lds + (bufoff) + ldsw + _i * 8192), 16, 0, 0); } while (0)
; #define PG8_LDA(dst, b, h) do { _Pragma("unroll") for (int m = 0; m < 4; ++m) _Pragma("unroll") for (int k = 0; k < 2; ++k) dst[m][k] = *(const PG8_LAS bf16x8*)(lds + PG8_SA(b, h) + aoff + m * 2048 + k * 1024); } while (0)
; #define PG8_LDB(dst, b, h) do { _Pragma("unroll") for (int n = 0; n < 2; ++n) _Pragma("unroll") for (int k = 0; k < 2; ++k) dst[n][k] = *(const PG8_LAS bf16x8*)(lds + PG8_SB(b, h) + boff + n * 2048 + k * 1024); } while (0)
; #define PG8_MMA(ai, bj, At, Bt) do { __builtin_amdgcn_s_setprio(1); _Pragma("unroll") for (int m = 0; m < 4; ++m) _Pragma("unroll") for (int n = 0; n < 2; ++n) _Pragma("unroll") for (int k = 0; k < 2; ++k) \
;         acc[ai][bj][m][n] = __builtin_amdgcn_mfma_f32_16x16x32_bf16(Bt[n][k], At[m][k], acc[ai][bj][m][n], 0, 0, 0); __builtin_amdgcn_s_setprio(0); } while (0)
; #define PG8_WAIT_V(n) asm volatile("s_waitcnt vmcnt(" #n ")" ::: "memory")
; #define PG8_WAIT_L(n) asm volatile("s_waitcnt lgkmcnt(" #n ")" ::: "memory")
; #define PG8_BAR __builtin_amdgcn_s_barrier()
; #define PG8_SCHED __builtin_amdgcn_sched_barrier(0)
; template <class Epi, class Sched, bool ALIGN_EPI = false, bool SP2 = false>
; __device__ __forceinline__ void gemm_phase(PG8_LAS unsigned char* lds, const Gemm g, const Sched& S, const Epi& E) {
;     ...
;             PG8_WAIT_V(8); PG8_WAIT_L(0); PG8_BAR; PG8_MMA(1, 0, At, B0); PG8_MMA(1, 1, At, B1); PG8_BAR; PG8_SCHED;
;             PG8_LDB(B0, 1, 0); PG8_LDB(B1, 1, 1); PG8_SCHED; PG8_LDA(At, 1, 0); PG8_STAGE(PG8_SA(0, 1), a2 + hstep, voffA);
;             PG8_WAIT_V(8); PG8_WAIT_L(0); PG8_BAR; PG8_MMA(0, 0, At, B0); PG8_MMA(0, 1, At, B1); PG8_BAR; PG8_SCHED;
;             PG8_LDA(At, 1, 1); PG8_STAGE(PG8_SB(1, 0), b3, voffB); PG8_STAGE(PG8_SB(1, 1), b3 + hstep, voffB); PG8_STAGE(PG8_SA(1, 0), a3, voffA);
;             PG8_WAIT_V(8); PG8_WAIT_L(0); PG8_BAR; PG8_MMA(1, 0, At, B0); PG8_MMA(1, 1, At, B1); PG8_BAR; PG8_SCHED;
;     ...
;         if constexpr (ALIGN_EPI) { if (wr == 0) PG8_BAR; }
	ds_read_b128 v[140:143], v254 offset:32768
	ds_read_b128 v[168:171], v254 offset:33792
	ds_read_b128 v[172:175], v254 offset:34816
	ds_read_b128 v[176:179], v254 offset:35840
	ds_read_b128 v[180:183], v254 offset:49152
	ds_read_b128 v[184:187], v254 offset:50176
	ds_read_b128 v[188:191], v254 offset:51200
	ds_read_b128 v[210:213], v254 offset:52224
	s_add_u32 s18, s18, 0x40000
	s_addc_u32 s19, s19, 0
	s_mov_b32 m0, s33
	ds_read_b128 v[214:217], v165 offset:32768
	ds_read_b128 v[218:221], v165 offset:33792
	ds_read_b128 v[222:225], v165 offset:34816
	ds_read_b128 v[226:229], v165 offset:35840
	ds_read_b128 v[230:233], v165 offset:36864
	ds_read_b128 v[234:237], v165 offset:37888
	ds_read_b128 v[238:241], v165 offset:38912
	ds_read_b128 v[242:245], v165 offset:39936
	global_load_lds_dwordx4 v134, s[18:19]
	s_mov_b32 m0, s34
	s_nop 0
	global_load_lds_dwordx4 v130, s[18:19]
	s_waitcnt vmcnt(8)
	s_waitcnt lgkmcnt(0)
	s_barrier
	s_setprio 1
	v_mfma_f32_16x16x32_bf16 v[124:127], v[140:143], v[214:217], v[124:127]
	v_mfma_f32_16x16x32_bf16 v[116:119], v[172:175], v[214:217], v[116:119]
	v_mfma_f32_16x16x32_bf16 v[108:111], v[140:143], v[222:225], v[108:111]
	v_mfma_f32_16x16x32_bf16 v[100:103], v[172:175], v[222:225], v[100:103]
	v_mfma_f32_16x16x32_bf16 v[92:95], v[140:143], v[230:233], v[92:95]
	v_mfma_f32_16x16x32_bf16 v[84:87], v[172:175], v[230:233], v[84:87]
	v_mfma_f32_16x16x32_bf16 v[76:79], v[140:143], v[238:241], v[76:79]
	v_mfma_f32_16x16x32_bf16 v[68:71], v[172:175], v[238:241], v[68:71]
	v_mfma_f32_16x16x32_bf16 v[124:127], v[168:171], v[218:221], v[124:127]
	v_mfma_f32_16x16x32_bf16 v[116:119], v[176:179], v[218:221], v[116:119]
	v_mfma_f32_16x16x32_bf16 v[108:111], v[168:171], v[226:229], v[108:111]
	v_mfma_f32_16x16x32_bf16 v[100:103], v[176:179], v[226:229], v[100:103]
	v_mfma_f32_16x16x32_bf16 v[92:95], v[168:171], v[234:237], v[92:95]
	v_mfma_f32_16x16x32_bf16 v[84:87], v[176:179], v[234:237], v[84:87]
	v_mfma_f32_16x16x32_bf16 v[76:79], v[168:171], v[242:245], v[76:79]
	v_mfma_f32_16x16x32_bf16 v[68:71], v[176:179], v[242:245], v[68:71]
	v_mfma_f32_16x16x32_bf16 v[120:123], v[180:183], v[214:217], v[120:123]
	v_mfma_f32_16x16x32_bf16 v[112:115], v[188:191], v[214:217], v[112:115]
	v_mfma_f32_16x16x32_bf16 v[104:107], v[180:183], v[222:225], v[104:107]
	v_mfma_f32_16x16x32_bf16 v[96:99], v[188:191], v[222:225], v[96:99]
	v_mfma_f32_16x16x32_bf16 v[88:91], v[180:183], v[230:233], v[88:91]
	v_mfma_f32_16x16x32_bf16 v[80:83], v[188:191], v[230:233], v[80:83]
	v_mfma_f32_16x16x32_bf16 v[72:75], v[180:183], v[238:241], v[72:75]
	v_mfma_f32_16x16x32_bf16 v[64:67], v[188:191], v[238:241], v[64:67]
	v_mfma_f32_16x16x32_bf16 v[120:123], v[184:187], v[218:221], v[120:123]
	v_mfma_f32_16x16x32_bf16 v[112:115], v[210:213], v[218:221], v[112:115]
	v_mfma_f32_16x16x32_bf16 v[104:107], v[184:187], v[226:229], v[104:107]
	v_mfma_f32_16x16x32_bf16 v[96:99], v[210:213], v[226:229], v[96:99]
	v_mfma_f32_16x16x32_bf16 v[88:91], v[184:187], v[234:237], v[88:91]
	v_mfma_f32_16x16x32_bf16 v[80:83], v[210:213], v[234:237], v[80:83]
	v_mfma_f32_16x16x32_bf16 v[72:75], v[184:187], v[242:245], v[72:75]
	v_mfma_f32_16x16x32_bf16 v[64:67], v[210:213], v[242:245], v[64:67]
	s_setprio 0
	s_barrier
	s_mov_b32 m0, s37
	s_add_u32 s16, s16, 0x40080
	s_addc_u32 s17, s17, 0
	ds_read_b128 v[214:217], v165 offset:49152
	ds_read_b128 v[218:221], v165 offset:50176
	ds_read_b128 v[222:225], v165 offset:51200
	ds_read_b128 v[226:229], v165 offset:52224
	ds_read_b128 v[230:233], v165 offset:53248
	ds_read_b128 v[234:237], v165 offset:54272
	ds_read_b128 v[238:241], v165 offset:55296
	ds_read_b128 v[242:245], v165 offset:56320
	s_add_u32 s98, s16, 0xfffc0000
	s_addc_u32 s99, s17, -1
	global_load_lds_dwordx4 v132, s[98:99]
	s_mov_b32 m0, s38
	s_nop 0
	global_load_lds_dwordx4 v128, s[98:99]
	s_mov_b32 m0, s41
	s_nop 0
	global_load_lds_dwordx4 v132, s[16:17]
	s_mov_b32 m0, s42
	s_nop 0
	global_load_lds_dwordx4 v128, s[16:17]
	s_mov_b32 m0, s39
	s_nop 0
	s_add_u32 s100, s18, 0xfffc0080
	s_addc_u32 s101, s19, -1
	global_load_lds_dwordx4 v134, s[100:101]
	s_mov_b32 m0, s40
	s_nop 0
	global_load_lds_dwordx4 v130, s[100:101]
	s_waitcnt vmcnt(8)
	s_waitcnt lgkmcnt(0)
	s_barrier
	s_setprio 1
	v_mfma_f32_16x16x32_bf16 v[60:63], v[140:143], v[214:217], v[60:63]
	v_mfma_f32_16x16x32_bf16 v[52:55], v[172:175], v[214:217], v[52:55]
	v_mfma_f32_16x16x32_bf16 v[44:47], v[140:143], v[222:225], v[44:47]
	v_mfma_f32_16x16x32_bf16 v[36:39], v[172:175], v[222:225], v[36:39]
	v_mfma_f32_16x16x32_bf16 v[28:31], v[140:143], v[230:233], v[28:31]
	v_mfma_f32_16x16x32_bf16 v[20:23], v[172:175], v[230:233], v[20:23]
	v_mfma_f32_16x16x32_bf16 v[12:15], v[140:143], v[238:241], v[12:15]
	v_mfma_f32_16x16x32_bf16 v[4:7], v[172:175], v[238:241], v[4:7]
	v_mfma_f32_16x16x32_bf16 v[60:63], v[168:171], v[218:221], v[60:63]
	v_mfma_f32_16x16x32_bf16 v[52:55], v[176:179], v[218:221], v[52:55]
	v_mfma_f32_16x16x32_bf16 v[44:47], v[168:171], v[226:229], v[44:47]
	v_mfma_f32_16x16x32_bf16 v[36:39], v[176:179], v[226:229], v[36:39]
	v_mfma_f32_16x16x32_bf16 v[28:31], v[168:171], v[234:237], v[28:31]
	v_mfma_f32_16x16x32_bf16 v[20:23], v[176:179], v[234:237], v[20:23]
	v_mfma_f32_16x16x32_bf16 v[12:15], v[168:171], v[242:245], v[12:15]
	v_mfma_f32_16x16x32_bf16 v[4:7], v[176:179], v[242:245], v[4:7]
	v_mfma_f32_16x16x32_bf16 v[56:59], v[180:183], v[214:217], v[56:59]
	v_mfma_f32_16x16x32_bf16 v[48:51], v[188:191], v[214:217], v[48:51]
	v_mfma_f32_16x16x32_bf16 v[40:43], v[180:183], v[222:225], v[40:43]
	v_mfma_f32_16x16x32_bf16 v[32:35], v[188:191], v[222:225], v[32:35]
	v_mfma_f32_16x16x32_bf16 v[24:27], v[180:183], v[230:233], v[24:27]
	v_mfma_f32_16x16x32_bf16 v[16:19], v[188:191], v[230:233], v[16:19]
	v_mfma_f32_16x16x32_bf16 v[8:11], v[180:183], v[238:241], v[8:11]
	v_mfma_f32_16x16x32_bf16 v[0:3], v[188:191], v[238:241], v[0:3]
	v_mfma_f32_16x16x32_bf16 v[56:59], v[184:187], v[218:221], v[56:59]
	v_mfma_f32_16x16x32_bf16 v[48:51], v[210:213], v[218:221], v[48:51]
	v_mfma_f32_16x16x32_bf16 v[40:43], v[184:187], v[226:229], v[40:43]
	v_mfma_f32_16x16x32_bf16 v[32:35], v[210:213], v[226:229], v[32:35]
	v_mfma_f32_16x16x32_bf16 v[24:27], v[184:187], v[234:237], v[24:27]
	v_mfma_f32_16x16x32_bf16 v[16:19], v[210:213], v[234:237], v[16:19]
	v_mfma_f32_16x16x32_bf16 v[8:11], v[184:187], v[242:245], v[8:11]
	v_mfma_f32_16x16x32_bf16 v[0:3], v[210:213], v[242:245], v[0:3]
	s_setprio 0
	s_barrier
	s_add_i32 s53, s53, 2
	s_add_u32 s14, s14, 0x100
	s_addc_u32 s15, s15, 0
	s_add_u32 s51, s51, 0x100
	s_addc_u32 s52, s52, 0
	s_cmp_gt_u32 s53, 13
	s_cbranch_scc0 .LBB0_446
	s_andn2_b64 vcc, s[2:3], s[8:9]
	s_and_b64 vcc, vcc, exec
	s_cbranch_vccz .LBB0_449
	s_barrier
; __device__ __forceinline__ unsigned cvt_pk_bf16(float lo, float hi) { unsigned r; asm volatile("v_cvt_pk_bf16_f32 %0, %1, %2" : "=v"(r) : "v"(lo), "v"(hi)); return r; }
;     __device__ __forceinline__ void operator()(const f32x4 (&acc)[2][2][4][2], const Unit& u, int ui, int wr, int wc, int fr, int fq) const {
;     ...
;         const int row0 = u.pm * BM + wr * 64 + fr, col0 = u.pn * HALF + wc * 32 + 8 * fq;
;         float rs[2][4];
; #pragma unroll
;         for (int ai = 0; ai < 2; ++ai)
; #pragma unroll
;             for (int m = 0; m < 4; ++m) rs[ai][m] = row_rstd(lds, ui, ai * HALF + wr * 64 + m * 16 + fr);
; #pragma unroll
;         for (int ai = 0; ai < 2; ++ai)
; #pragma unroll
;             for (int m = 0; m < 4; ++m) { const float r = rs[ai][m]; const int row = row0 + ai * HALF + m * 16;
;                 const float c1 = r * -1.44269504089f, r2 = r * r; u32x4 w;
; #pragma unroll
;                 for (int n = 0; n < 2; ++n)
; #pragma unroll
;                     for (int p = 0; p < 2; ++p) { const f32x2 g = (f32x2){acc[ai][0][m][n][2 * p], acc[ai][0][m][n][2 * p + 1]}, uu = (f32x2){acc[ai][1][m][n][2 * p], acc[ai][1][m][n][2 * p + 1]};
;                         const f32x2 t = g * c1; f32x2 d; d.x = __builtin_amdgcn_exp2f(t.x); d.y = __builtin_amdgcn_exp2f(t.y); d = d + 1.0f;
;                         f32x2 q; q.x = __builtin_amdgcn_rcpf(d.x); q.y = __builtin_amdgcn_rcpf(d.y);
;                         const f32x2 hh = (g * uu) * (q * r2); w[2 * n + p] = cvt_pk_bf16(hh.x, hh.y); }
;                 __builtin_nontemporal_store(w, (u32x4*)(H + (size_t)row * ldh + col0)); }
.LBB0_449:
	v_mov_b32_e32 v140, v147
	v_mov_b32_e32 v167, v164
	v_pk_mul_f32 v[120:121], v[124:125], v[120:121]
	v_add_u32_e32 v171, s35, v140
	v_lshlrev_b32_e32 v140, 2, v171
	v_lshl_add_u32 v140, s48, 10, v140
	v_add_u32_e32 v140, 0x20400, v140
	ds_read2_b32 v[168:169], v140 offset1:16
	ds_read2_b32 v[162:163], v140 offset0:32 offset1:48
	ds_read2_b32 v[142:143], v140 offset0:128 offset1:144
	ds_read2_b32 v[140:141], v140 offset0:160 offset1:176
	v_pk_mul_f32 v[122:123], v[126:127], v[122:123]
	s_waitcnt lgkmcnt(0)
	v_mul_f32_e32 v172, 0xbfb8aa3b, v168
	v_pk_mul_f32 v[174:175], v[124:125], v[172:173] op_sel_hi:[1,0]
	v_pk_mul_f32 v[124:125], v[126:127], v[172:173] op_sel_hi:[1,0]
	v_exp_f32_e32 v174, v174
	v_exp_f32_e32 v175, v175
	v_exp_f32_e32 v124, v124
	v_exp_f32_e32 v125, v125
	v_mul_f32_e32 v168, v168, v168
	v_pk_add_f32 v[174:175], v[174:175], 1.0 op_sel_hi:[1,0]
	v_pk_mul_f32 v[112:113], v[116:117], v[112:113]
	v_rcp_f32_e32 v174, v174
	v_rcp_f32_e32 v175, v175
	v_pk_add_f32 v[124:125], v[124:125], 1.0 op_sel_hi:[1,0]
	v_pk_mul_f32 v[114:115], v[118:119], v[114:115]
	v_rcp_f32_e32 v124, v124
	v_rcp_f32_e32 v125, v125
	v_pk_mul_f32 v[126:127], v[168:169], v[174:175] op_sel_hi:[0,1]
	v_pk_mul_f32 v[120:121], v[120:121], v[126:127]
	v_pk_mul_f32 v[126:127], v[116:117], v[172:173] op_sel_hi:[1,0]
	v_pk_mul_f32 v[124:125], v[168:169], v[124:125] op_sel_hi:[0,1]
	v_exp_f32_e32 v126, v126
	v_exp_f32_e32 v127, v127
	v_pk_mul_f32 v[122:123], v[122:123], v[124:125]
	v_pk_mul_f32 v[124:125], v[118:119], v[172:173] op_sel_hi:[1,0]
	v_cvt_pk_bf16_f32 v120, v120, v121
	v_cvt_pk_bf16_f32 v121, v122, v123
	v_pk_add_f32 v[122:123], v[126:127], 1.0 op_sel_hi:[1,0]
	v_exp_f32_e32 v124, v124
	v_exp_f32_e32 v125, v125
	v_rcp_f32_e32 v122, v122
	v_rcp_f32_e32 v123, v123
	s_lshl_b32 s5, s47, 7
	v_pk_add_f32 v[116:117], v[124:125], 1.0 op_sel_hi:[1,0]
	s_or_b32 s5, s5, s36
	v_rcp_f32_e32 v116, v116
	v_rcp_f32_e32 v117, v117
	v_pk_mul_f32 v[118:119], v[168:169], v[122:123] op_sel_hi:[0,1]
	v_pk_mul_f32 v[112:113], v[112:113], v[118:119]
	v_mul_f32_e32 v118, 0xbfb8aa3b, v169
	v_cvt_pk_bf16_f32 v122, v112, v113
	v_pk_mul_f32 v[112:113], v[168:169], v[116:117] op_sel_hi:[0,1]
	v_pk_mul_f32 v[124:125], v[108:109], v[118:119] op_sel_hi:[1,0]
	v_lshl_add_u32 v170, v167, 3, s5
	v_pk_mul_f32 v[112:113], v[114:115], v[112:113]
	v_exp_f32_e32 v124, v124
	v_exp_f32_e32 v125, v125
	v_lshl_add_u32 v167, s46, 8, v171
	v_ashrrev_i32_e32 v171, 31, v170
	v_cvt_pk_bf16_f32 v123, v112, v113
	v_mov_b64_e32 v[112:113], s[20:21]
	v_pk_mul_f32 v[104:105], v[108:109], v[104:105]
	v_pk_mul_f32 v[108:109], v[110:111], v[118:119] op_sel_hi:[1,0]
	v_mad_i64_i32 v[116:117], s[14:15], v167, s59, v[112:113]
	v_lshlrev_b64 v[114:115], 1, v[170:171]
	v_exp_f32_e32 v108, v108
	v_exp_f32_e32 v109, v109
	v_lshl_add_u64 v[116:117], v[116:117], 0, v[114:115]
	global_store_dwordx4 v[116:117], v[120:123], off nt
	v_mul_f32_e32 v116, v169, v169
	v_pk_add_f32 v[108:109], v[108:109], 1.0 op_sel_hi:[1,0]
	v_pk_add_f32 v[120:121], v[124:125], 1.0 op_sel_hi:[1,0]
	v_rcp_f32_e32 v108, v108
	v_rcp_f32_e32 v120, v120
	v_rcp_f32_e32 v121, v121
	v_rcp_f32_e32 v109, v109
	v_pk_mul_f32 v[106:107], v[110:111], v[106:107]
	v_pk_mul_f32 v[96:97], v[100:101], v[96:97]
	v_pk_mul_f32 v[110:111], v[116:117], v[120:121] op_sel_hi:[0,1]
	v_pk_mul_f32 v[104:105], v[104:105], v[110:111]
	v_pk_mul_f32 v[110:111], v[100:101], v[118:119] op_sel_hi:[1,0]
	v_pk_mul_f32 v[108:109], v[116:117], v[108:109] op_sel_hi:[0,1]
	v_exp_f32_e32 v110, v110
	v_exp_f32_e32 v111, v111
	v_pk_mul_f32 v[106:107], v[106:107], v[108:109]
	v_pk_mul_f32 v[108:109], v[102:103], v[118:119] op_sel_hi:[1,0]
	v_cvt_pk_bf16_f32 v104, v104, v105
	v_cvt_pk_bf16_f32 v105, v106, v107
	v_pk_add_f32 v[106:107], v[110:111], 1.0 op_sel_hi:[1,0]
	v_exp_f32_e32 v108, v108
	v_exp_f32_e32 v109, v109
	v_rcp_f32_e32 v106, v106
	v_rcp_f32_e32 v107, v107
	v_pk_mul_f32 v[98:99], v[102:103], v[98:99]
	v_pk_add_f32 v[100:101], v[108:109], 1.0 op_sel_hi:[1,0]
	v_pk_mul_f32 v[88:89], v[92:93], v[88:89]
	v_rcp_f32_e32 v100, v100
	v_rcp_f32_e32 v101, v101
	v_pk_mul_f32 v[102:103], v[116:117], v[106:107] op_sel_hi:[0,1]
	v_pk_mul_f32 v[96:97], v[96:97], v[102:103]
	v_pk_mul_f32 v[90:91], v[94:95], v[90:91]
	v_cvt_pk_bf16_f32 v106, v96, v97
	v_pk_mul_f32 v[96:97], v[116:117], v[100:101] op_sel_hi:[0,1]
	v_pk_mul_f32 v[96:97], v[98:99], v[96:97]
	v_mul_f32_e32 v98, 0xbfb8aa3b, v162
	v_pk_mul_f32 v[100:101], v[92:93], v[98:99] op_sel_hi:[1,0]
	v_pk_mul_f32 v[92:93], v[94:95], v[98:99] op_sel_hi:[1,0]
	v_exp_f32_e32 v100, v100
	v_exp_f32_e32 v101, v101
	v_exp_f32_e32 v92, v92
	v_exp_f32_e32 v93, v93
	v_cvt_pk_bf16_f32 v107, v96, v97
	v_pk_add_f32 v[100:101], v[100:101], 1.0 op_sel_hi:[1,0]
	v_add_u32_e32 v96, 16, v167
	v_rcp_f32_e32 v100, v100
	v_rcp_f32_e32 v101, v101
	v_mad_i64_i32 v[96:97], s[14:15], v96, s59, v[112:113]
	v_pk_add_f32 v[92:93], v[92:93], 1.0 op_sel_hi:[1,0]
	v_lshl_add_u64 v[96:97], v[96:97], 0, v[114:115]
	v_rcp_f32_e32 v92, v92
	v_rcp_f32_e32 v93, v93
	global_store_dwordx4 v[96:97], v[104:107], off nt
	v_mul_f32_e32 v96, v162, v162
	v_pk_mul_f32 v[94:95], v[96:97], v[100:101] op_sel_hi:[0,1]
	v_pk_mul_f32 v[88:89], v[88:89], v[94:95]
	v_pk_mul_f32 v[94:95], v[84:85], v[98:99] op_sel_hi:[1,0]
	v_pk_mul_f32 v[92:93], v[96:97], v[92:93] op_sel_hi:[0,1]
	v_exp_f32_e32 v94, v94
	v_exp_f32_e32 v95, v95
	v_pk_mul_f32 v[90:91], v[90:91], v[92:93]
	v_pk_mul_f32 v[92:93], v[86:87], v[98:99] op_sel_hi:[1,0]
	v_cvt_pk_bf16_f32 v88, v88, v89
	v_cvt_pk_bf16_f32 v89, v90, v91
	v_pk_add_f32 v[90:91], v[94:95], 1.0 op_sel_hi:[1,0]
	v_exp_f32_e32 v92, v92
; __device__ __forceinline__ unsigned cvt_pk_bf16(float lo, float hi) { unsigned r; asm volatile("v_cvt_pk_bf16_f32 %0, %1, %2" : "=v"(r) : "v"(lo), "v"(hi)); return r; }
;     __device__ __forceinline__ void operator()(const f32x4 (&acc)[2][2][4][2], const Unit& u, int ui, int wr, int wc, int fr, int fq) const {
;     ...
;             for (int m = 0; m < 4; ++m) { const float r = rs[ai][m]; const int row = row0 + ai * HALF + m * 16;
;                 const float c1 = r * -1.44269504089f, r2 = r * r; u32x4 w;
; #pragma unroll
;                 for (int n = 0; n < 2; ++n)
; #pragma unroll
;                     for (int p = 0; p < 2; ++p) { const f32x2 g = (f32x2){acc[ai][0][m][n][2 * p], acc[ai][0][m][n][2 * p + 1]}, uu = (f32x2){acc[ai][1][m][n][2 * p], acc[ai][1][m][n][2 * p + 1]};
;                         const f32x2 t = g * c1; f32x2 d; d.x = __builtin_amdgcn_exp2f(t.x); d.y = __builtin_amdgcn_exp2f(t.y); d = d + 1.0f;
;                         f32x2 q; q.x = __builtin_amdgcn_rcpf(d.x); q.y = __builtin_amdgcn_rcpf(d.y);
;                         const f32x2 hh = (g * uu) * (q * r2); w[2 * n + p] = cvt_pk_bf16(hh.x, hh.y); }
;                 __builtin_nontemporal_store(w, (u32x4*)(H + (size_t)row * ldh + col0)); }
	v_exp_f32_e32 v93, v93
	v_rcp_f32_e32 v90, v90
	v_rcp_f32_e32 v91, v91
	v_pk_mul_f32 v[80:81], v[84:85], v[80:81]
	v_pk_add_f32 v[84:85], v[92:93], 1.0 op_sel_hi:[1,0]
	v_pk_mul_f32 v[82:83], v[86:87], v[82:83]
	v_rcp_f32_e32 v84, v84
	v_rcp_f32_e32 v85, v85
	v_pk_mul_f32 v[86:87], v[96:97], v[90:91] op_sel_hi:[0,1]
	v_pk_mul_f32 v[80:81], v[80:81], v[86:87]
	v_pk_mul_f32 v[72:73], v[76:77], v[72:73]
	v_cvt_pk_bf16_f32 v90, v80, v81
	v_pk_mul_f32 v[80:81], v[96:97], v[84:85] op_sel_hi:[0,1]
	v_pk_mul_f32 v[80:81], v[82:83], v[80:81]
	v_mul_f32_e32 v82, 0xbfb8aa3b, v163
	v_pk_mul_f32 v[84:85], v[76:77], v[82:83] op_sel_hi:[1,0]
	v_pk_mul_f32 v[76:77], v[78:79], v[82:83] op_sel_hi:[1,0]
	v_exp_f32_e32 v84, v84
	v_exp_f32_e32 v85, v85
	v_exp_f32_e32 v76, v76
	v_exp_f32_e32 v77, v77
	v_cvt_pk_bf16_f32 v91, v80, v81
	v_pk_add_f32 v[84:85], v[84:85], 1.0 op_sel_hi:[1,0]
	v_add_u32_e32 v80, 32, v167
	v_rcp_f32_e32 v84, v84
	v_rcp_f32_e32 v85, v85
	v_mad_i64_i32 v[80:81], s[14:15], v80, s59, v[112:113]
	v_pk_add_f32 v[76:77], v[76:77], 1.0 op_sel_hi:[1,0]
	v_lshl_add_u64 v[80:81], v[80:81], 0, v[114:115]
	v_rcp_f32_e32 v76, v76
	v_rcp_f32_e32 v77, v77
	global_store_dwordx4 v[80:81], v[88:91], off nt
	v_mul_f32_e32 v80, v163, v163
	v_pk_mul_f32 v[74:75], v[78:79], v[74:75]
	v_pk_mul_f32 v[78:79], v[80:81], v[84:85] op_sel_hi:[0,1]
	v_pk_mul_f32 v[72:73], v[72:73], v[78:79]
	v_pk_mul_f32 v[78:79], v[68:69], v[82:83] op_sel_hi:[1,0]
	v_pk_mul_f32 v[76:77], v[80:81], v[76:77] op_sel_hi:[0,1]
	v_exp_f32_e32 v78, v78
	v_exp_f32_e32 v79, v79
	v_pk_mul_f32 v[74:75], v[74:75], v[76:77]
	v_pk_mul_f32 v[76:77], v[70:71], v[82:83] op_sel_hi:[1,0]
	v_cvt_pk_bf16_f32 v72, v72, v73
	v_cvt_pk_bf16_f32 v73, v74, v75
	v_pk_add_f32 v[74:75], v[78:79], 1.0 op_sel_hi:[1,0]
	v_exp_f32_e32 v76, v76
	v_exp_f32_e32 v77, v77
	v_rcp_f32_e32 v74, v74
	v_rcp_f32_e32 v75, v75
	v_pk_mul_f32 v[64:65], v[68:69], v[64:65]
	v_pk_add_f32 v[68:69], v[76:77], 1.0 op_sel_hi:[1,0]
	v_pk_mul_f32 v[66:67], v[70:71], v[66:67]
	v_rcp_f32_e32 v68, v68
	v_rcp_f32_e32 v69, v69
	v_pk_mul_f32 v[70:71], v[80:81], v[74:75] op_sel_hi:[0,1]
	v_pk_mul_f32 v[64:65], v[64:65], v[70:71]
	v_pk_mul_f32 v[56:57], v[60:61], v[56:57]
	v_cvt_pk_bf16_f32 v74, v64, v65
	v_pk_mul_f32 v[64:65], v[80:81], v[68:69] op_sel_hi:[0,1]
	v_pk_mul_f32 v[64:65], v[66:67], v[64:65]
	v_mul_f32_e32 v66, 0xbfb8aa3b, v142
	v_pk_mul_f32 v[68:69], v[60:61], v[66:67] op_sel_hi:[1,0]
	v_pk_mul_f32 v[60:61], v[62:63], v[66:67] op_sel_hi:[1,0]
	v_exp_f32_e32 v68, v68
	v_exp_f32_e32 v69, v69
	v_exp_f32_e32 v60, v60
	v_exp_f32_e32 v61, v61
	v_cvt_pk_bf16_f32 v75, v64, v65
	v_pk_add_f32 v[68:69], v[68:69], 1.0 op_sel_hi:[1,0]
	v_add_u32_e32 v64, 48, v167
	v_rcp_f32_e32 v68, v68
	v_rcp_f32_e32 v69, v69
	v_mad_i64_i32 v[64:65], s[14:15], v64, s59, v[112:113]
	v_pk_add_f32 v[60:61], v[60:61], 1.0 op_sel_hi:[1,0]
	v_lshl_add_u64 v[64:65], v[64:65], 0, v[114:115]
	v_rcp_f32_e32 v60, v60
	v_rcp_f32_e32 v61, v61
	global_store_dwordx4 v[64:65], v[72:75], off nt
	v_add_u32_e32 v65, 0x80, v167
	v_mul_f32_e32 v64, v142, v142
	v_pk_mul_f32 v[58:59], v[62:63], v[58:59]
	v_pk_mul_f32 v[62:63], v[64:65], v[68:69] op_sel_hi:[0,1]
	v_pk_mul_f32 v[56:57], v[56:57], v[62:63]
	v_pk_mul_f32 v[62:63], v[52:53], v[66:67] op_sel_hi:[1,0]
	v_pk_mul_f32 v[60:61], v[64:65], v[60:61] op_sel_hi:[0,1]
	v_exp_f32_e32 v62, v62
	v_exp_f32_e32 v63, v63
	v_pk_mul_f32 v[58:59], v[58:59], v[60:61]
	v_pk_mul_f32 v[60:61], v[54:55], v[66:67] op_sel_hi:[1,0]
	v_cvt_pk_bf16_f32 v56, v56, v57
	v_cvt_pk_bf16_f32 v57, v58, v59
	v_pk_add_f32 v[58:59], v[62:63], 1.0 op_sel_hi:[1,0]
	v_exp_f32_e32 v60, v60
	v_exp_f32_e32 v61, v61
	v_rcp_f32_e32 v58, v58
	v_rcp_f32_e32 v59, v59
	v_pk_mul_f32 v[48:49], v[52:53], v[48:49]
	v_pk_add_f32 v[52:53], v[60:61], 1.0 op_sel_hi:[1,0]
	v_pk_mul_f32 v[50:51], v[54:55], v[50:51]
	v_rcp_f32_e32 v52, v52
	v_rcp_f32_e32 v53, v53
	v_pk_mul_f32 v[54:55], v[64:65], v[58:59] op_sel_hi:[0,1]
	v_pk_mul_f32 v[48:49], v[48:49], v[54:55]
	v_pk_mul_f32 v[40:41], v[44:45], v[40:41]
	v_cvt_pk_bf16_f32 v58, v48, v49
	v_pk_mul_f32 v[48:49], v[64:65], v[52:53] op_sel_hi:[0,1]
	v_pk_mul_f32 v[48:49], v[50:51], v[48:49]
	v_mul_f32_e32 v50, 0xbfb8aa3b, v143
	v_pk_mul_f32 v[52:53], v[44:45], v[50:51] op_sel_hi:[1,0]
	v_pk_mul_f32 v[44:45], v[46:47], v[50:51] op_sel_hi:[1,0]
	v_exp_f32_e32 v52, v52
	v_exp_f32_e32 v53, v53
	v_exp_f32_e32 v44, v44
	v_exp_f32_e32 v45, v45
	v_cvt_pk_bf16_f32 v59, v48, v49
	v_pk_add_f32 v[52:53], v[52:53], 1.0 op_sel_hi:[1,0]
	v_mad_i64_i32 v[48:49], s[14:15], v65, s59, v[112:113]
	v_rcp_f32_e32 v52, v52
	v_rcp_f32_e32 v53, v53
	v_pk_add_f32 v[44:45], v[44:45], 1.0 op_sel_hi:[1,0]
	v_lshl_add_u64 v[48:49], v[48:49], 0, v[114:115]
	v_rcp_f32_e32 v44, v44
	v_rcp_f32_e32 v45, v45
	global_store_dwordx4 v[48:49], v[56:59], off nt
	v_mul_f32_e32 v48, v143, v143
	v_pk_mul_f32 v[42:43], v[46:47], v[42:43]
; __device__ __forceinline__ unsigned cvt_pk_bf16(float lo, float hi) { unsigned r; asm volatile("v_cvt_pk_bf16_f32 %0, %1, %2" : "=v"(r) : "v"(lo), "v"(hi)); return r; }
; #define PG8_BAR __builtin_amdgcn_s_barrier()
;     __device__ __forceinline__ void operator()(const f32x4 (&acc)[2][2][4][2], const Unit& u, int ui, int wr, int wc, int fr, int fq) const {
;     ...
;             for (int m = 0; m < 4; ++m) { const float r = rs[ai][m]; const int row = row0 + ai * HALF + m * 16;
;                 const float c1 = r * -1.44269504089f, r2 = r * r; u32x4 w;
; #pragma unroll
;                 for (int n = 0; n < 2; ++n)
; #pragma unroll
;                     for (int p = 0; p < 2; ++p) { const f32x2 g = (f32x2){acc[ai][0][m][n][2 * p], acc[ai][0][m][n][2 * p + 1]}, uu = (f32x2){acc[ai][1][m][n][2 * p], acc[ai][1][m][n][2 * p + 1]};
;                         const f32x2 t = g * c1; f32x2 d; d.x = __builtin_amdgcn_exp2f(t.x); d.y = __builtin_amdgcn_exp2f(t.y); d = d + 1.0f;
;                         f32x2 q; q.x = __builtin_amdgcn_rcpf(d.x); q.y = __builtin_amdgcn_rcpf(d.y);
;                         const f32x2 hh = (g * uu) * (q * r2); w[2 * n + p] = cvt_pk_bf16(hh.x, hh.y); }
;                 __builtin_nontemporal_store(w, (u32x4*)(H + (size_t)row * ldh + col0)); }
; template <class Epi, class Sched, bool ALIGN_EPI = false, bool SP2 = false>
; __device__ __forceinline__ void gemm_phase(PG8_LAS unsigned char* lds, const Gemm g, const Sched& S, const Epi& E) {
;     ...
;         cur = nxt; cA = nA; cB = nB; ++ui;
;         if constexpr (ALIGN_EPI) { if (wr == 1) PG8_BAR; }
	v_pk_mul_f32 v[46:47], v[48:49], v[52:53] op_sel_hi:[0,1]
	v_pk_mul_f32 v[40:41], v[40:41], v[46:47]
	v_pk_mul_f32 v[46:47], v[36:37], v[50:51] op_sel_hi:[1,0]
	v_pk_mul_f32 v[44:45], v[48:49], v[44:45] op_sel_hi:[0,1]
	v_exp_f32_e32 v46, v46
	v_exp_f32_e32 v47, v47
	v_pk_mul_f32 v[42:43], v[42:43], v[44:45]
	v_pk_mul_f32 v[44:45], v[38:39], v[50:51] op_sel_hi:[1,0]
	v_cvt_pk_bf16_f32 v40, v40, v41
	v_cvt_pk_bf16_f32 v41, v42, v43
	v_pk_add_f32 v[42:43], v[46:47], 1.0 op_sel_hi:[1,0]
	v_exp_f32_e32 v44, v44
	v_exp_f32_e32 v45, v45
	v_rcp_f32_e32 v42, v42
	v_rcp_f32_e32 v43, v43
	v_pk_mul_f32 v[32:33], v[36:37], v[32:33]
	v_pk_add_f32 v[36:37], v[44:45], 1.0 op_sel_hi:[1,0]
	v_pk_mul_f32 v[34:35], v[38:39], v[34:35]
	v_rcp_f32_e32 v36, v36
	v_rcp_f32_e32 v37, v37
	v_pk_mul_f32 v[38:39], v[48:49], v[42:43] op_sel_hi:[0,1]
	v_pk_mul_f32 v[32:33], v[32:33], v[38:39]
	v_pk_mul_f32 v[24:25], v[28:29], v[24:25]
	v_cvt_pk_bf16_f32 v42, v32, v33
	v_pk_mul_f32 v[32:33], v[48:49], v[36:37] op_sel_hi:[0,1]
	v_pk_mul_f32 v[32:33], v[34:35], v[32:33]
	v_mul_f32_e32 v34, 0xbfb8aa3b, v140
	v_pk_mul_f32 v[36:37], v[28:29], v[34:35] op_sel_hi:[1,0]
	v_pk_mul_f32 v[28:29], v[30:31], v[34:35] op_sel_hi:[1,0]
	v_exp_f32_e32 v36, v36
	v_exp_f32_e32 v37, v37
	v_exp_f32_e32 v28, v28
	v_exp_f32_e32 v29, v29
	v_cvt_pk_bf16_f32 v43, v32, v33
	v_pk_add_f32 v[36:37], v[36:37], 1.0 op_sel_hi:[1,0]
	v_add_u32_e32 v32, 0x90, v167
	v_rcp_f32_e32 v36, v36
	v_rcp_f32_e32 v37, v37
	v_mad_i64_i32 v[32:33], s[14:15], v32, s59, v[112:113]
	v_pk_add_f32 v[28:29], v[28:29], 1.0 op_sel_hi:[1,0]
	v_lshl_add_u64 v[32:33], v[32:33], 0, v[114:115]
	v_rcp_f32_e32 v28, v28
	v_rcp_f32_e32 v29, v29
	global_store_dwordx4 v[32:33], v[40:43], off nt
	v_mul_f32_e32 v32, v140, v140
	v_pk_mul_f32 v[26:27], v[30:31], v[26:27]
	v_pk_mul_f32 v[30:31], v[32:33], v[36:37] op_sel_hi:[0,1]
	v_pk_mul_f32 v[24:25], v[24:25], v[30:31]
	v_pk_mul_f32 v[30:31], v[20:21], v[34:35] op_sel_hi:[1,0]
	v_pk_mul_f32 v[28:29], v[32:33], v[28:29] op_sel_hi:[0,1]
	v_exp_f32_e32 v30, v30
	v_exp_f32_e32 v31, v31
	v_pk_mul_f32 v[26:27], v[26:27], v[28:29]
	v_pk_mul_f32 v[28:29], v[22:23], v[34:35] op_sel_hi:[1,0]
	v_cvt_pk_bf16_f32 v24, v24, v25
	v_cvt_pk_bf16_f32 v25, v26, v27
	v_pk_add_f32 v[26:27], v[30:31], 1.0 op_sel_hi:[1,0]
	v_exp_f32_e32 v28, v28
	v_exp_f32_e32 v29, v29
	v_rcp_f32_e32 v26, v26
	v_rcp_f32_e32 v27, v27
	v_pk_mul_f32 v[16:17], v[20:21], v[16:17]
	v_pk_add_f32 v[20:21], v[28:29], 1.0 op_sel_hi:[1,0]
	v_pk_mul_f32 v[18:19], v[22:23], v[18:19]
	v_rcp_f32_e32 v20, v20
	v_rcp_f32_e32 v21, v21
	v_pk_mul_f32 v[22:23], v[32:33], v[26:27] op_sel_hi:[0,1]
	v_pk_mul_f32 v[16:17], v[16:17], v[22:23]
	v_pk_mul_f32 v[8:9], v[12:13], v[8:9]
	v_cvt_pk_bf16_f32 v26, v16, v17
	v_pk_mul_f32 v[16:17], v[32:33], v[20:21] op_sel_hi:[0,1]
	v_pk_mul_f32 v[16:17], v[18:19], v[16:17]
	v_mul_f32_e32 v18, 0xbfb8aa3b, v141
	v_pk_mul_f32 v[20:21], v[12:13], v[18:19] op_sel_hi:[1,0]
	v_pk_mul_f32 v[12:13], v[14:15], v[18:19] op_sel_hi:[1,0]
	v_exp_f32_e32 v20, v20
	v_exp_f32_e32 v21, v21
	v_exp_f32_e32 v12, v12
	v_exp_f32_e32 v13, v13
	v_cvt_pk_bf16_f32 v27, v16, v17
	v_pk_add_f32 v[20:21], v[20:21], 1.0 op_sel_hi:[1,0]
	v_add_u32_e32 v16, 0xa0, v167
	v_rcp_f32_e32 v20, v20
	v_rcp_f32_e32 v21, v21
	v_mad_i64_i32 v[16:17], s[14:15], v16, s59, v[112:113]
	v_pk_add_f32 v[12:13], v[12:13], 1.0 op_sel_hi:[1,0]
	v_lshl_add_u64 v[16:17], v[16:17], 0, v[114:115]
	v_rcp_f32_e32 v12, v12
	v_rcp_f32_e32 v13, v13
	global_store_dwordx4 v[16:17], v[24:27], off nt
	v_mul_f32_e32 v16, v141, v141
	v_pk_mul_f32 v[10:11], v[14:15], v[10:11]
	v_pk_mul_f32 v[14:15], v[16:17], v[20:21] op_sel_hi:[0,1]
	v_pk_mul_f32 v[8:9], v[8:9], v[14:15]
	v_pk_mul_f32 v[14:15], v[4:5], v[18:19] op_sel_hi:[1,0]
	v_pk_mul_f32 v[12:13], v[16:17], v[12:13] op_sel_hi:[0,1]
	v_exp_f32_e32 v14, v14
	v_exp_f32_e32 v15, v15
	v_pk_mul_f32 v[10:11], v[10:11], v[12:13]
	v_pk_mul_f32 v[12:13], v[6:7], v[18:19] op_sel_hi:[1,0]
	v_cvt_pk_bf16_f32 v8, v8, v9
	v_cvt_pk_bf16_f32 v9, v10, v11
	v_pk_add_f32 v[10:11], v[14:15], 1.0 op_sel_hi:[1,0]
	v_exp_f32_e32 v12, v12
	v_exp_f32_e32 v13, v13
	v_rcp_f32_e32 v10, v10
	v_rcp_f32_e32 v11, v11
	v_pk_mul_f32 v[0:1], v[4:5], v[0:1]
	v_pk_add_f32 v[4:5], v[12:13], 1.0 op_sel_hi:[1,0]
	v_pk_mul_f32 v[2:3], v[6:7], v[2:3]
	v_rcp_f32_e32 v4, v4
	v_rcp_f32_e32 v5, v5
	v_pk_mul_f32 v[6:7], v[16:17], v[10:11] op_sel_hi:[0,1]
	v_pk_mul_f32 v[0:1], v[0:1], v[6:7]
	s_andn2_b64 vcc, exec, s[8:9]
	v_cvt_pk_bf16_f32 v10, v0, v1
	v_pk_mul_f32 v[0:1], v[16:17], v[4:5] op_sel_hi:[0,1]
	v_pk_mul_f32 v[0:1], v[2:3], v[0:1]
	s_mov_b64 s[8:9], -1
	v_cvt_pk_bf16_f32 v11, v0, v1
	v_add_u32_e32 v0, 0xb0, v167
	v_mad_i64_i32 v[0:1], s[14:15], v0, s59, v[112:113]
	v_lshl_add_u64 v[0:1], v[0:1], 0, v[114:115]
	global_store_dwordx4 v[0:1], v[8:11], off nt
	s_cbranch_vccnz .LBB0_442
	s_andn2_b64 vcc, exec, s[0:1]
	s_cbranch_vccnz .LBB0_441
	s_branch .LBB0_441
